# v27 + LayerNorm gain/bias vectors hoisted out of the row loop in the first LN phase, waits recounted
# speedup vs baseline: 1.0020x; 1.0020x over previous
; DEV void ln_finish(float4 (&v)[4], float* dstf, bf16_t* dstb, const float* g, const float* b, int lane) {
;     ...
;   for (int i = 0; i < 4; ++i) {
;     const int c = (i * 64 + lane) * 4;
;     const float4 gg = *(const float4*)(g + c), bb = *(const float4*)(b + c);
; DEV void phase_ln(const Params& p, const float* g, const float* b, bool write_xb, bool do_mem) {
;     ...
;   for (int r = gw; r < NTOK; r += 2 * nw) {
;     const int r2 = r + nw;
;     float4 v0[4], v1[4];
;     float* row0 = p.out + (size_t)r * DM;
;     float* row1 = p.out + (size_t)(r2 < NTOK ? r2 : r) * DM;
;     ln_load(row0, v0, lane);
;     ln_load(row1, v1, lane);
.LBB0_339:
	s_and_saveexec_b64 s[62:63], s[6:7]
	s_cbranch_execz .LBB0_352
	s_mov_b64 s[64:65], 0
	v_mov_b64_e32 v[44:45], v[42:43]
	v_mov_b64_e32 v[46:47], v[40:41]
	v_mov_b64_e32 v[48:49], v[38:39]
	v_mov_b32_e32 v71, v28
	global_load_dwordx4 v[128:131], v[32:33], off
	global_load_dwordx4 v[132:135], v[32:33], off offset:1024
	global_load_dwordx4 v[136:139], v[32:33], off offset:2048
	global_load_dwordx4 v[140:143], v[32:33], off offset:3072
	global_load_dwordx4 v[144:147], v[34:35], off
	global_load_dwordx4 v[148:151], v[34:35], off offset:1024
	global_load_dwordx4 v[152:155], v[34:35], off offset:2048
	global_load_dwordx4 v[156:159], v[34:35], off offset:3072
	s_waitcnt vmcnt(0)
	s_branch .LBB0_342

; DEV void ln_finish(float4 (&v)[4], float* dstf, bf16_t* dstb, const float* g, const float* b, int lane) {
;   float s = 0.f;
; #pragma unroll
;   for (int i = 0; i < 4; ++i) s += v[i].x + v[i].y + v[i].z + v[i].w;
;   const float mu = wave_sum_dpp(s) * (1.f / 1024.f);
;   float q = 0.f;
; #pragma unroll
;   for (int i = 0; i < 4; ++i) {
;     v[i].x -= mu; v[i].y -= mu; v[i].z -= mu; v[i].w -= mu;
;     q += v[i].x * v[i].x + v[i].y * v[i].y + v[i].z * v[i].z + v[i].w * v[i].w;
;   }
;   const float rs = rsqrtf(wave_sum_dpp(q) * (1.f / 1024.f) + 1e-5f);
; #pragma unroll
;   for (int i = 0; i < 4; ++i) {
;     const int c = (i * 64 + lane) * 4;
;     const float4 gg = *(const float4*)(g + c), bb = *(const float4*)(b + c);
;     float4 o;
;     o.x = v[i].x * rs * gg.x + bb.x; o.y = v[i].y * rs * gg.y + bb.y;
;     o.z = v[i].z * rs * gg.z + bb.z; o.w = v[i].w * rs * gg.w + bb.w;
;     if (dstf) *(float4*)(dstf + c) = o;
;     if (dstb) { uint2 u; u.x = pack2(o.x, o.y); u.y = pack2(o.z, o.w); *(uint2*)(dstb + c) = u; }
;   }
; }
; DEV void phase_ln(const Params& p, const float* g, const float* b, bool write_xb, bool do_mem) {
;   const int lane = threadIdx.x & 63;
;   const int gw = blockIdx.x * 4 + (threadIdx.x >> 6), nw = gridDim.x * 4;
;   bf16_t* xb = (bf16_t*)(p.ws + O_XB);
;   for (int r = gw; r < NTOK; r += 2 * nw) {
;     const int r2 = r + nw;
;     float4 v0[4], v1[4];
;     float* row0 = p.out + (size_t)r * DM;
;     float* row1 = p.out + (size_t)(r2 < NTOK ? r2 : r) * DM;
;     ln_load(row0, v0, lane);
;     ln_load(row1, v1, lane);
;     ln_finish(v0, row0, write_xb ? xb + (size_t)r * DM : nullptr, g, b, lane);
.LBB0_342:
	v_add_u32_e32 v0, s90, v71
	v_cmp_gt_i32_e64 s[10:11], s91, v0
	s_nop 1
	v_cndmask_b32_e64 v0, v71, v0, s[10:11]
	v_ashrrev_i32_e32 v1, 31, v0
	v_lshlrev_b64 v[0:1], 12, v[0:1]
	v_lshl_add_u64 v[50:51], v[36:37], 0, v[0:1]
	global_load_dwordx4 v[12:15], v[50:51], off
	global_load_dwordx4 v[8:11], v[50:51], off offset:1024
	global_load_dwordx4 v[4:7], v[50:51], off offset:2048
	global_load_dwordx4 v[0:3], v[50:51], off offset:3072
	global_load_dwordx4 v[16:19], v[44:45], off offset:1024
	global_load_dwordx4 v[52:55], v[44:45], off
	s_waitcnt vmcnt(1)
	v_mov_b32_e32 v21, v16
	s_waitcnt vmcnt(0)
	v_mov_b32_e32 v20, v52
	v_mov_b32_e32 v22, v53
	v_mov_b32_e32 v23, v17
	v_pk_add_f32 v[20:21], v[20:21], v[22:23]
	v_mov_b32_e32 v22, v54
	v_mov_b32_e32 v23, v18
	v_pk_add_f32 v[20:21], v[20:21], v[22:23]
	v_mov_b32_e32 v22, v55
	v_mov_b32_e32 v23, v19
	v_pk_add_f32 v[56:57], v[20:21], v[22:23]
	global_load_dwordx4 v[58:61], v[44:45], off offset:-1024
	global_load_dwordx4 v[62:65], v[44:45], off offset:-2048
	v_mov_b32_e32 v20, v128
	v_mov_b32_e32 v21, v129
	v_mov_b32_e32 v22, v130
	v_mov_b32_e32 v23, v131
	v_mov_b32_e32 v24, v144
	v_mov_b32_e32 v25, v145
	v_mov_b32_e32 v26, v146
	v_mov_b32_e32 v27, v147
	s_waitcnt vmcnt(1)
	v_mov_b32_e32 v73, v58
	s_waitcnt vmcnt(0)
	v_mov_b32_e32 v72, v62
	v_mov_b32_e32 v74, v63
	v_mov_b32_e32 v75, v59
	v_pk_add_f32 v[72:73], v[72:73], v[74:75]
	v_mov_b32_e32 v74, v64
	v_mov_b32_e32 v75, v60
	v_pk_add_f32 v[72:73], v[72:73], v[74:75]
	v_mov_b32_e32 v74, v65
	v_mov_b32_e32 v75, v61
	v_pk_add_f32 v[72:73], v[72:73], v[74:75]
	s_nop 0
	v_add_f32_e32 v72, 0, v72
	v_add_f32_e32 v72, v72, v73
	v_add_f32_e32 v56, v72, v56
	v_add_f32_e32 v56, v56, v57
	s_nop 1
	v_add_f32_dpp v56, v56, v56 row_ror:8 row_mask:0xf bank_mask:0xf bound_ctrl:1
	s_nop 1
	v_add_f32_dpp v56, v56, v56 row_ror:4 row_mask:0xf bank_mask:0xf bound_ctrl:1
	s_nop 1
	v_add_f32_dpp v56, v56, v56 row_ror:2 row_mask:0xf bank_mask:0xf bound_ctrl:1
	s_nop 1
	v_add_f32_dpp v56, v56, v56 row_ror:1 row_mask:0xf bank_mask:0xf bound_ctrl:1
	s_nop 0
	v_readlane_b32 s56, v56, 16
	v_readlane_b32 s66, v56, 48
	v_readlane_b32 s12, v56, 0
	v_readlane_b32 s13, v56, 32
	v_mov_b32_e32 v56, s56
	v_mov_b32_e32 v57, s66
	v_pk_add_f32 v[56:57], s[12:13], v[56:57]
	s_nop 0
	v_add_f32_e32 v56, v56, v57
	v_mul_f32_e32 v72, 0x3a800000, v56
	v_pk_add_f32 v[74:75], v[62:63], v[72:73] op_sel_hi:[1,0] neg_lo:[0,1] neg_hi:[0,1]
	v_pk_add_f32 v[58:59], v[58:59], v[72:73] op_sel_hi:[1,0] neg_lo:[0,1] neg_hi:[0,1]
	v_mov_b32_e32 v62, v75
	v_mov_b32_e32 v63, v59
	v_pk_add_f32 v[76:77], v[64:65], v[72:73] op_sel_hi:[1,0] neg_lo:[0,1] neg_hi:[0,1]
	v_pk_add_f32 v[56:57], v[60:61], v[72:73] op_sel_hi:[1,0] neg_lo:[0,1] neg_hi:[0,1]
	v_mov_b32_e32 v60, v74
	v_mov_b32_e32 v61, v58
	v_pk_mul_f32 v[62:63], v[62:63], v[62:63]
	s_nop 0
	v_pk_fma_f32 v[60:61], v[60:61], v[60:61], v[62:63]
	v_mov_b32_e32 v62, v76
	v_mov_b32_e32 v63, v56
	v_pk_fma_f32 v[60:61], v[62:63], v[62:63], v[60:61]
	v_mov_b32_e32 v62, v77
	v_mov_b32_e32 v63, v57
	v_pk_fma_f32 v[64:65], v[62:63], v[62:63], v[60:61]
	v_pk_add_f32 v[62:63], v[52:53], v[72:73] op_sel_hi:[1,0] neg_lo:[0,1] neg_hi:[0,1]
	v_pk_add_f32 v[60:61], v[54:55], v[72:73] op_sel_hi:[1,0] neg_lo:[0,1] neg_hi:[0,1]
	v_pk_add_f32 v[54:55], v[16:17], v[72:73] op_sel_hi:[1,0] neg_lo:[0,1] neg_hi:[0,1]
	v_pk_add_f32 v[52:53], v[18:19], v[72:73] op_sel_hi:[1,0] neg_lo:[0,1] neg_hi:[0,1]
	v_mov_b32_e32 v18, v55
	v_mov_b32_e32 v19, v63
	v_mov_b32_e32 v16, v54
	v_mov_b32_e32 v17, v62
	v_pk_mul_f32 v[18:19], v[18:19], v[18:19]
	s_nop 0
	v_pk_fma_f32 v[16:17], v[16:17], v[16:17], v[18:19]
	v_mov_b32_e32 v18, v52
	v_mov_b32_e32 v19, v60
	v_pk_fma_f32 v[16:17], v[18:19], v[18:19], v[16:17]
	v_mov_b32_e32 v18, v53
	v_mov_b32_e32 v19, v61
	v_pk_fma_f32 v[16:17], v[18:19], v[18:19], v[16:17]
	v_add_f32_e32 v18, v64, v65
	v_add_f32_e32 v17, v17, v18
	v_add_f32_e32 v16, v16, v17
	s_nop 1
	v_add_f32_dpp v16, v16, v16 row_ror:8 row_mask:0xf bank_mask:0xf bound_ctrl:1
	s_nop 1
	v_add_f32_dpp v16, v16, v16 row_ror:4 row_mask:0xf bank_mask:0xf bound_ctrl:1
	s_nop 1
	v_add_f32_dpp v16, v16, v16 row_ror:2 row_mask:0xf bank_mask:0xf bound_ctrl:1
	s_nop 1
	v_add_f32_dpp v16, v16, v16 row_ror:1 row_mask:0xf bank_mask:0xf bound_ctrl:1
	s_nop 0
	v_readlane_b32 s56, v16, 16
	v_readlane_b32 s66, v16, 48
	v_readlane_b32 s12, v16, 0
	v_readlane_b32 s13, v16, 32
	v_mov_b32_e32 v16, s56
	v_mov_b32_e32 v17, s66
	v_pk_add_f32 v[16:17], s[12:13], v[16:17]
	v_cmp_ne_u32_e64 s[12:13], 1, v66
	v_add_f32_e32 v16, v16, v17
	v_fmamk_f32 v16, v16, 0x3a800000, v29
	v_cmp_gt_f32_e32 vcc, s3, v16
	v_mul_f32_e32 v17, 0x4b800000, v16
	s_nop 0
	v_cndmask_b32_e32 v16, v16, v17, vcc
	v_rsq_f32_e32 v16, v16
	s_nop 0
	v_mul_f32_e32 v17, 0x45800000, v16
	v_cndmask_b32_e32 v64, v16, v17, vcc
	v_pk_mul_f32 v[16:17], v[74:75], v[64:65] op_sel_hi:[1,0]
	v_pk_mul_f32 v[18:19], v[76:77], v[64:65] op_sel_hi:[1,0]
	v_pk_fma_f32 v[16:17], v[20:21], v[16:17], v[24:25]
	v_pk_fma_f32 v[18:19], v[22:23], v[18:19], v[26:27]
	s_andn2_b64 vcc, exec, s[4:5]
	s_cbranch_vccnz .LBB0_344
	global_store_dwordx4 v[44:45], v[16:19], off offset:-2048
.LBB0_344:
	v_lshl_add_u64 v[20:21], v[48:49], 0, v[30:31]
	s_nop 0
	v_cvt_pk_bf16_f32 v16, v16, v17
	v_cvt_pk_bf16_f32 v17, v18, v19
	v_add_co_u32_e32 v18, vcc, 0x1b00000, v20
	v_mov_b32_e32 v65, v64
	s_nop 0
	v_addc_co_u32_e32 v19, vcc, 0, v21, vcc
	global_store_dwordx2 v[18:19], v[16:17], off
	v_mov_b32_e32 v16, v132
	v_mov_b32_e32 v17, v133
	v_mov_b32_e32 v18, v134
	v_mov_b32_e32 v19, v135
	s_nop 0
	v_mov_b32_e32 v22, v148
	v_mov_b32_e32 v23, v149
	v_mov_b32_e32 v24, v150
	v_mov_b32_e32 v25, v151
	v_pk_mul_f32 v[26:27], v[58:59], v[64:65]
	v_pk_mul_f32 v[56:57], v[56:57], v[64:65]
	s_and_b64 vcc, exec, s[12:13]
	v_pk_fma_f32 v[16:17], v[26:27], v[16:17], v[22:23]
	v_pk_fma_f32 v[18:19], v[56:57], v[18:19], v[24:25]
	s_cbranch_vccnz .LBB0_346
	global_store_dwordx4 v[44:45], v[16:19], off offset:-1024
; DEV void ln_finish(float4 (&v)[4], float* dstf, bf16_t* dstb, const float* g, const float* b, int lane) {
;     ...
;   for (int i = 0; i < 4; ++i) {
;     const int c = (i * 64 + lane) * 4;
;     const float4 gg = *(const float4*)(g + c), bb = *(const float4*)(b + c);
;     float4 o;
;     o.x = v[i].x * rs * gg.x + bb.x; o.y = v[i].y * rs * gg.y + bb.y;
;     o.z = v[i].z * rs * gg.z + bb.z; o.w = v[i].w * rs * gg.w + bb.w;
;     if (dstf) *(float4*)(dstf + c) = o;
;     if (dstb) { uint2 u; u.x = pack2(o.x, o.y); u.y = pack2(o.z, o.w); *(uint2*)(dstb + c) = u; }
.LBB0_346:
	s_nop 1
	v_cvt_pk_bf16_f32 v16, v16, v17
	v_cvt_pk_bf16_f32 v17, v18, v19
	v_add_co_u32_e32 v18, vcc, 0x1b00000, v20
	v_pk_mul_f32 v[26:27], v[62:63], v[64:65]
	s_nop 0
	v_addc_co_u32_e32 v19, vcc, 0, v21, vcc
	global_store_dwordx2 v[18:19], v[16:17], off offset:512
	v_mov_b32_e32 v16, v136
	v_mov_b32_e32 v17, v137
	v_mov_b32_e32 v18, v138
	v_mov_b32_e32 v19, v139
	s_nop 0
	v_mov_b32_e32 v22, v152
	v_mov_b32_e32 v23, v153
	v_mov_b32_e32 v24, v154
	v_mov_b32_e32 v25, v155
	v_pk_mul_f32 v[56:57], v[60:61], v[64:65]
	s_and_b64 vcc, exec, s[12:13]
	v_pk_fma_f32 v[16:17], v[26:27], v[16:17], v[22:23]
	v_pk_fma_f32 v[18:19], v[56:57], v[18:19], v[24:25]
	s_cbranch_vccnz .LBB0_348
	global_store_dwordx4 v[44:45], v[16:19], off
.LBB0_348:
	s_nop 1
	v_cvt_pk_bf16_f32 v16, v16, v17
	v_cvt_pk_bf16_f32 v17, v18, v19
	v_add_co_u32_e32 v18, vcc, 0x1b00000, v20
	v_pk_mul_f32 v[26:27], v[54:55], v[64:65]
	s_nop 0
	v_addc_co_u32_e32 v19, vcc, 0, v21, vcc
	global_store_dwordx2 v[18:19], v[16:17], off offset:1024
	v_mov_b32_e32 v16, v140
	v_mov_b32_e32 v17, v141
	v_mov_b32_e32 v18, v142
	v_mov_b32_e32 v19, v143
	s_nop 0
	v_mov_b32_e32 v22, v156
	v_mov_b32_e32 v23, v157
	v_mov_b32_e32 v24, v158
	v_mov_b32_e32 v25, v159
	v_pk_mul_f32 v[52:53], v[52:53], v[64:65]
	s_and_b64 vcc, exec, s[12:13]
	v_pk_fma_f32 v[16:17], v[26:27], v[16:17], v[22:23]
	v_pk_fma_f32 v[18:19], v[52:53], v[18:19], v[24:25]
	s_cbranch_vccnz .LBB0_350
	global_store_dwordx4 v[44:45], v[16:19], off offset:1024
; DEV void ln_finish(float4 (&v)[4], float* dstf, bf16_t* dstb, const float* g, const float* b, int lane) {
;   float s = 0.f;
; #pragma unroll
;   for (int i = 0; i < 4; ++i) s += v[i].x + v[i].y + v[i].z + v[i].w;
;   const float mu = wave_sum_dpp(s) * (1.f / 1024.f);
;   float q = 0.f;
; #pragma unroll
;   for (int i = 0; i < 4; ++i) {
;     v[i].x -= mu; v[i].y -= mu; v[i].z -= mu; v[i].w -= mu;
;     q += v[i].x * v[i].x + v[i].y * v[i].y + v[i].z * v[i].z + v[i].w * v[i].w;
;   }
;   const float rs = rsqrtf(wave_sum_dpp(q) * (1.f / 1024.f) + 1e-5f);
; #pragma unroll
;   for (int i = 0; i < 4; ++i) {
;     const int c = (i * 64 + lane) * 4;
;     const float4 gg = *(const float4*)(g + c), bb = *(const float4*)(b + c);
;     float4 o;
;     o.x = v[i].x * rs * gg.x + bb.x; o.y = v[i].y * rs * gg.y + bb.y;
;     o.z = v[i].z * rs * gg.z + bb.z; o.w = v[i].w * rs * gg.w + bb.w;
;     if (dstf) *(float4*)(dstf + c) = o;
;     if (dstb) { uint2 u; u.x = pack2(o.x, o.y); u.y = pack2(o.z, o.w); *(uint2*)(dstb + c) = u; }
;   }
; }
; DEV void phase_ln(const Params& p, const float* g, const float* b, bool write_xb, bool do_mem) {
;   const int lane = threadIdx.x & 63;
;   const int gw = blockIdx.x * 4 + (threadIdx.x >> 6), nw = gridDim.x * 4;
;   bf16_t* xb = (bf16_t*)(p.ws + O_XB);
;   for (int r = gw; r < NTOK; r += 2 * nw) {
;     const int r2 = r + nw;
;     float4 v0[4], v1[4];
;     float* row0 = p.out + (size_t)r * DM;
;     float* row1 = p.out + (size_t)(r2 < NTOK ? r2 : r) * DM;
;     ln_load(row0, v0, lane);
;     ln_load(row1, v1, lane);
;     ln_finish(v0, row0, write_xb ? xb + (size_t)r * DM : nullptr, g, b, lane);
;     if (r2 < NTOK) ln_finish(v1, row1, write_xb ? xb + (size_t)r2 * DM : nullptr, g, b, lane);
.LBB0_350:
	s_nop 1
	v_cvt_pk_bf16_f32 v16, v16, v17
	v_cvt_pk_bf16_f32 v17, v18, v19
	v_add_co_u32_e32 v18, vcc, 0x1b00000, v20
	s_nop 1
	v_addc_co_u32_e32 v19, vcc, 0, v21, vcc
	global_store_dwordx2 v[18:19], v[16:17], off offset:1536
	s_and_saveexec_b64 s[12:13], s[10:11]
	s_cbranch_execz .LBB0_341
	v_mov_b32_e32 v16, v12
	v_mov_b32_e32 v17, v8
	v_mov_b32_e32 v18, v13
	v_mov_b32_e32 v19, v9
	v_pk_add_f32 v[16:17], v[16:17], v[18:19]
	v_mov_b32_e32 v18, v14
	v_mov_b32_e32 v19, v10
	v_pk_add_f32 v[16:17], v[16:17], v[18:19]
	v_mov_b32_e32 v18, v15
	v_mov_b32_e32 v19, v11
	v_pk_add_f32 v[16:17], v[16:17], v[18:19]
	v_mov_b32_e32 v18, v5
	v_add_f32_e32 v16, 0, v16
	v_add_f32_e32 v52, v16, v17
	v_mov_b32_e32 v16, v4
	v_mov_b32_e32 v17, v0
	v_mov_b32_e32 v19, v1
	v_pk_add_f32 v[24:25], v[16:17], v[18:19]
	v_mov_b32_e32 v16, v128
	v_mov_b32_e32 v17, v129
	v_mov_b32_e32 v18, v130
	v_mov_b32_e32 v19, v131
	v_mov_b32_e32 v20, v144
	v_mov_b32_e32 v21, v145
	v_mov_b32_e32 v22, v146
	v_mov_b32_e32 v23, v147
	v_mov_b32_e32 v26, v6
	v_mov_b32_e32 v27, v2
	v_pk_add_f32 v[24:25], v[24:25], v[26:27]
	v_mov_b32_e32 v26, v7
	v_mov_b32_e32 v27, v3
	v_pk_add_f32 v[24:25], v[24:25], v[26:27]
	s_nop 0
	v_add_f32_e32 v24, v52, v24
	v_add_f32_e32 v24, v24, v25
	s_nop 1
	v_add_f32_dpp v24, v24, v24 row_ror:8 row_mask:0xf bank_mask:0xf bound_ctrl:1
	s_nop 1
	v_add_f32_dpp v24, v24, v24 row_ror:4 row_mask:0xf bank_mask:0xf bound_ctrl:1
	s_nop 1
	v_add_f32_dpp v24, v24, v24 row_ror:2 row_mask:0xf bank_mask:0xf bound_ctrl:1
	s_nop 1
	v_add_f32_dpp v24, v24, v24 row_ror:1 row_mask:0xf bank_mask:0xf bound_ctrl:1
	s_nop 0
	v_readlane_b32 s56, v24, 16
	v_readlane_b32 s66, v24, 48
	v_readlane_b32 s10, v24, 0
	v_readlane_b32 s11, v24, 32
	v_mov_b32_e32 v24, s56
	v_mov_b32_e32 v25, s66
	v_pk_add_f32 v[24:25], s[10:11], v[24:25]
	s_nop 0
	v_add_f32_e32 v24, v24, v25
	v_mul_f32_e32 v24, 0x3a800000, v24
	v_pk_add_f32 v[12:13], v[12:13], v[24:25] op_sel_hi:[1,0] neg_lo:[0,1] neg_hi:[0,1]
	v_pk_add_f32 v[8:9], v[8:9], v[24:25] op_sel_hi:[1,0] neg_lo:[0,1] neg_hi:[0,1]
	v_mov_b32_e32 v52, v13
	v_mov_b32_e32 v53, v9
	v_pk_add_f32 v[14:15], v[14:15], v[24:25] op_sel_hi:[1,0] neg_lo:[0,1] neg_hi:[0,1]
	v_pk_add_f32 v[10:11], v[10:11], v[24:25] op_sel_hi:[1,0] neg_lo:[0,1] neg_hi:[0,1]
	v_mov_b32_e32 v26, v12
	v_mov_b32_e32 v27, v8
	v_pk_mul_f32 v[52:53], v[52:53], v[52:53]
	v_mov_b32_e32 v54, v15
	v_pk_fma_f32 v[26:27], v[26:27], v[26:27], v[52:53]
	v_mov_b32_e32 v52, v14
	v_mov_b32_e32 v53, v10
	v_mov_b32_e32 v55, v11
	v_pk_fma_f32 v[26:27], v[52:53], v[52:53], v[26:27]
	v_pk_add_f32 v[52:53], v[4:5], v[24:25] op_sel_hi:[1,0] neg_lo:[0,1] neg_hi:[0,1]
	v_pk_add_f32 v[56:57], v[0:1], v[24:25] op_sel_hi:[1,0] neg_lo:[0,1] neg_hi:[0,1]
	v_pk_fma_f32 v[26:27], v[54:55], v[54:55], v[26:27]
	v_pk_add_f32 v[54:55], v[6:7], v[24:25] op_sel_hi:[1,0] neg_lo:[0,1] neg_hi:[0,1]
	v_pk_add_f32 v[24:25], v[2:3], v[24:25] op_sel_hi:[1,0] neg_lo:[0,1] neg_hi:[0,1]
	v_mov_b32_e32 v2, v57
	v_mov_b32_e32 v3, v53
	v_mov_b32_e32 v0, v56
	v_mov_b32_e32 v1, v52
	v_pk_mul_f32 v[2:3], v[2:3], v[2:3]
	v_mov_b32_e32 v4, v25
	v_pk_fma_f32 v[0:1], v[0:1], v[0:1], v[2:3]
	v_mov_b32_e32 v2, v24
	v_mov_b32_e32 v3, v54
	v_mov_b32_e32 v5, v55
	v_pk_fma_f32 v[0:1], v[2:3], v[2:3], v[0:1]
	v_add_f32_e32 v2, v26, v27
	v_pk_fma_f32 v[0:1], v[4:5], v[4:5], v[0:1]
	v_lshl_add_u64 v[4:5], v[46:47], 0, v[30:31]
	v_add_f32_e32 v1, v1, v2
	v_add_f32_e32 v0, v0, v1
	s_nop 1
	v_add_f32_dpp v0, v0, v0 row_ror:8 row_mask:0xf bank_mask:0xf bound_ctrl:1
	s_nop 1
	v_add_f32_dpp v0, v0, v0 row_ror:4 row_mask:0xf bank_mask:0xf bound_ctrl:1
	s_nop 1
	v_add_f32_dpp v0, v0, v0 row_ror:2 row_mask:0xf bank_mask:0xf bound_ctrl:1
	s_nop 1
	v_add_f32_dpp v0, v0, v0 row_ror:1 row_mask:0xf bank_mask:0xf bound_ctrl:1
	s_nop 0
	v_readlane_b32 s56, v0, 16
	v_readlane_b32 s66, v0, 48
	v_readlane_b32 s10, v0, 0
	v_readlane_b32 s11, v0, 32
	v_mov_b32_e32 v0, s56
	v_mov_b32_e32 v1, s66
	v_pk_add_f32 v[0:1], s[10:11], v[0:1]
	s_mov_b32 s10, 0x1b00000
	v_add_f32_e32 v0, v0, v1
	v_fmamk_f32 v0, v0, 0x3a800000, v29
	v_mul_f32_e32 v1, 0x4b800000, v0
	v_cmp_gt_f32_e32 vcc, s3, v0
	s_nop 1
	v_cndmask_b32_e32 v0, v0, v1, vcc
	v_rsq_f32_e32 v0, v0
	s_nop 0
	v_mul_f32_e32 v1, 0x45800000, v0
	v_cndmask_b32_e32 v26, v0, v1, vcc
	v_pk_mul_f32 v[0:1], v[12:13], v[26:27] op_sel_hi:[1,0]
	v_pk_mul_f32 v[2:3], v[14:15], v[26:27] op_sel_hi:[1,0]
	v_pk_fma_f32 v[0:1], v[16:17], v[0:1], v[20:21]
	v_pk_fma_f32 v[2:3], v[18:19], v[2:3], v[22:23]
	v_add_co_u32_e32 v12, vcc, s10, v4
	global_store_dwordx4 v[50:51], v[0:3], off
	s_nop 0
	v_addc_co_u32_e32 v13, vcc, 0, v5, vcc
	v_cvt_pk_bf16_f32 v0, v0, v1
	v_cvt_pk_bf16_f32 v1, v2, v3
	global_store_dwordx2 v[12:13], v[0:1], off
	v_mov_b32_e32 v0, v132
	v_mov_b32_e32 v1, v133
	v_mov_b32_e32 v2, v134
	v_mov_b32_e32 v3, v135
	s_nop 0
	v_mov_b32_e32 v4, v148
	v_mov_b32_e32 v5, v149
	v_mov_b32_e32 v6, v150
	v_mov_b32_e32 v7, v151
	v_pk_mul_f32 v[8:9], v[8:9], v[26:27] op_sel_hi:[1,0]
	v_pk_mul_f32 v[10:11], v[10:11], v[26:27] op_sel_hi:[1,0]
	v_pk_fma_f32 v[0:1], v[8:9], v[0:1], v[4:5]
	v_pk_fma_f32 v[2:3], v[10:11], v[2:3], v[6:7]
	global_store_dwordx4 v[50:51], v[0:3], off offset:1024
	v_pk_mul_f32 v[8:9], v[52:53], v[26:27] op_sel_hi:[1,0]
	v_pk_mul_f32 v[10:11], v[54:55], v[26:27] op_sel_hi:[1,0]
	v_cvt_pk_bf16_f32 v0, v0, v1
	v_cvt_pk_bf16_f32 v1, v2, v3
	global_store_dwordx2 v[12:13], v[0:1], off offset:512
	v_mov_b32_e32 v0, v136
	v_mov_b32_e32 v1, v137
	v_mov_b32_e32 v2, v138
	v_mov_b32_e32 v3, v139
	s_nop 0
	v_mov_b32_e32 v4, v152
	v_mov_b32_e32 v5, v153
	v_mov_b32_e32 v6, v154
	v_mov_b32_e32 v7, v155
	v_pk_fma_f32 v[0:1], v[8:9], v[0:1], v[4:5]
	v_pk_fma_f32 v[2:3], v[10:11], v[2:3], v[6:7]
	global_store_dwordx4 v[50:51], v[0:3], off offset:2048
	v_pk_mul_f32 v[8:9], v[56:57], v[26:27] op_sel_hi:[1,0]
	v_pk_mul_f32 v[10:11], v[24:25], v[26:27] op_sel_hi:[1,0]
	v_cvt_pk_bf16_f32 v0, v0, v1
	v_cvt_pk_bf16_f32 v1, v2, v3
	global_store_dwordx2 v[12:13], v[0:1], off offset:1024
	v_mov_b32_e32 v0, v140
	v_mov_b32_e32 v1, v141
	v_mov_b32_e32 v2, v142
	v_mov_b32_e32 v3, v143
	s_nop 0
	v_mov_b32_e32 v4, v156
	v_mov_b32_e32 v5, v157
	v_mov_b32_e32 v6, v158
	v_mov_b32_e32 v7, v159
	v_pk_fma_f32 v[0:1], v[8:9], v[0:1], v[4:5]
	v_pk_fma_f32 v[2:3], v[10:11], v[2:3], v[6:7]
	global_store_dwordx4 v[50:51], v[0:3], off offset:3072
	s_nop 1
	v_cvt_pk_bf16_f32 v0, v0, v1
	v_cvt_pk_bf16_f32 v1, v2, v3
	global_store_dwordx2 v[12:13], v[0:1], off offset:1536
	s_branch .LBB0_341
